# weight prep split: phase 0 converts only the in-proj A weights (plus a few); the other matrices are converted during in-proj A by the workgroups that have one tile fewer, after their last tile
# baseline (speedup 1.0000x reference)
.Lprep_chk:
	v_readlane_b32 s0, v254, 40
	v_readlane_b32 s1, v249, 25
	s_nop 0
	s_cmp_eq_u32 s0, 1
	s_cbranch_scc1 .Lprep_chk2
	s_cmp_eq_u32 s0, 16
	s_cbranch_scc0 .LBB0_627
.Lprep_chk2:
	s_cmp_lt_u32 s1, 0x200
	s_cbranch_scc1 .LBB0_627
	s_mov_b32 s32, 1
	s_branch .Lprep_go

.LBB0_489:
	v_readlane_b32 s20, v254, 24
	s_and_b64 vcc, exec, s[0:1]
	v_readlane_b32 s21, v254, 25
	s_cbranch_vccz .Lprep_chk
	s_mov_b32 s32, 0
.Lprep_go:
	v_mov_b32_e32 v58, v216
	v_readlane_b32 s1, v249, 25
	v_readfirstlane_b32 s0, v58
	s_ashr_i32 s0, s0, 6
	s_add_i32 s6, s0, s1
	s_cmp_eq_u32 s32, 0
	s_cbranch_scc1 .Lprep_s6
	s_addk_i32 s6, 0x1080
.Lprep_s6:
	s_mov_b64 s[4:5], s[82:83]
	s_mov_b32 s44, 0x1c1000
	s_mov_b32 s37, 0x151000
	s_mov_b32 s45, 0xe0000
	s_cmpk_gt_i32 s6, 0x367f
	v_and_b32_e32 v57, 63, v58
	s_cbranch_scc1 .LBB0_605
	v_readlane_b32 s2, v254, 36
	v_readlane_b32 s8, v254, 8
	s_mov_b32 s24, s2
	s_ashr_i32 s25, s2, 31
	s_mul_hi_i32 s1, s2, 0x3830000
	s_mul_i32 s2, s2, 0x3830000
	v_readlane_b32 s14, v254, 14
	v_readlane_b32 s3, v254, 37
	v_readlane_b32 s10, v254, 10
	v_readlane_b32 s15, v254, 15
	v_readlane_b32 s16, v254, 16
	v_readlane_b32 s17, v254, 17
	v_readlane_b32 s18, v254, 18
	v_readlane_b32 s20, v254, 20
	v_readlane_b32 s21, v254, 21
	s_add_u32 s2, s14, s2
	s_mulk_i32 s0, 0x2200
	v_readlane_b32 s11, v254, 11
	v_readlane_b32 s19, v254, 19
	s_addc_u32 s3, s15, s1
	s_add_i32 s7, s0, 0
	s_lshl_b64 s[0:1], s[24:25], 24
	s_lshl_b32 s10, s24, 10
	s_lshl_b64 s[20:21], s[24:25], 22
	s_lshl_b64 s[16:17], s[24:25], 23
	s_lshl_b32 s18, s24, 11
	v_readlane_b32 s24, v253, 5
	s_ashr_i32 s11, s10, 31
	s_ashr_i32 s19, s18, 31
	v_readlane_b32 s26, v253, 7
	v_readlane_b32 s27, v253, 8
	s_add_u32 s38, s26, s0
	v_readlane_b32 s12, v254, 12
	v_readlane_b32 s13, v254, 13
	v_readlane_b32 s22, v254, 22
	v_readlane_b32 s23, v254, 23
	s_addc_u32 s39, s27, s1
	v_readlane_b32 s9, v254, 9
	v_readlane_b32 s25, v253, 6
	s_add_u32 s8, s24, s0
	s_mov_b64 s[12:13], s[62:63]
	s_mov_b64 s[22:23], s[60:61]
	v_readlane_b32 s48, v249, 38
	s_addc_u32 s9, s25, s1
	s_lshl_b64 s[0:1], s[10:11], 2
	v_readlane_b32 s62, v249, 52
	v_readlane_b32 s63, v249, 53
	s_add_u32 s10, s62, s0
	v_readlane_b32 s60, v249, 50
	s_addc_u32 s11, s63, s1
	v_readlane_b32 s61, v249, 51
	s_mov_b64 s[62:63], s[12:13]
	s_add_u32 s12, s60, s20
	v_readlane_b32 s58, v249, 48
	s_addc_u32 s13, s61, s21
	v_readlane_b32 s59, v249, 49
	s_add_u32 s14, s58, s20
	v_readlane_b32 s56, v249, 46
	s_addc_u32 s15, s59, s21
	v_readlane_b32 s57, v249, 47
	s_add_u32 s16, s56, s16
	v_readlane_b32 s68, v249, 56
	s_addc_u32 s17, s57, s17
	s_lshl_b64 s[18:19], s[18:19], 2
	v_readlane_b32 s78, v250, 2
	v_readlane_b32 s79, v250, 3
	s_add_u32 s18, s78, s18
	v_readlane_b32 s54, v249, 44
	v_readlane_b32 s69, v249, 57
	v_readlane_b32 s70, v249, 58
	v_readlane_b32 s71, v249, 59
	v_readlane_b32 s72, v249, 60
	v_readlane_b32 s73, v249, 61
	v_readlane_b32 s74, v249, 62
	v_readlane_b32 s75, v249, 63
	v_readlane_b32 s76, v250, 0
	v_readlane_b32 s77, v250, 1
	s_addc_u32 s19, s79, s19
	v_readlane_b32 s55, v249, 45
	v_readlane_b32 s64, v254, 8
	s_add_u32 s20, s54, s20
	v_readlane_b32 s68, v254, 12
	s_addc_u32 s21, s55, s21
	s_mov_b64 s[60:61], s[22:23]
	v_readlane_b32 s69, v254, 13
	s_add_u32 s22, s68, s0
	s_addc_u32 s23, s69, s1
	s_waitcnt lgkmcnt(0)
	v_and_b32_e32 v2, 7, v58
	v_readlane_b32 s0, v249, 26
	v_lshlrev_b32_e32 v0, 4, v2
	v_readlane_b32 s1, v249, 27
	v_lshrrev_b32_e32 v34, 3, v57
	v_readlane_b32 s28, v253, 9
	v_lshl_add_u64 v[36:37], s[0:1], 0, v[0:1]
	v_readlane_b32 s0, v252, 17
	v_readlane_b32 s1, v252, 18
	v_readlane_b32 s29, v253, 10
	v_readlane_b32 s42, v250, 10
	v_lshl_add_u64 v[38:39], s[0:1], 0, v[0:1]
	v_readlane_b32 s0, v249, 28
	v_readlane_b32 s1, v249, 29
	v_readlane_b32 s80, v250, 4
	v_readlane_b32 s81, v250, 5
	v_lshl_add_u64 v[40:41], s[0:1], 0, v[0:1]
	v_readlane_b32 s0, v249, 30
	v_readlane_b32 s1, v249, 31
	v_readlane_b32 s40, v250, 8
	v_mul_u32_u24_e32 v3, 0x420, v2
	v_lshl_add_u64 v[42:43], s[0:1], 0, v[0:1]
	v_readlane_b32 s0, v249, 32
	v_readlane_b32 s1, v249, 33
	v_lshlrev_b32_e32 v4, 2, v34
	v_lshlrev_b32_e32 v61, 2, v2
	v_lshl_add_u64 v[44:45], s[0:1], 0, v[0:1]
	v_readlane_b32 s0, v249, 34
	v_readlane_b32 s1, v249, 35
	v_or_b32_e32 v2, 32, v34
	s_mov_b32 s33, 0x70000
	v_lshl_add_u64 v[46:47], s[0:1], 0, v[0:1]
	v_readlane_b32 s0, v249, 36
	v_readlane_b32 s1, v249, 37
	v_readlane_b32 s43, v250, 11
	s_mov_b32 s80, 0x24000
	v_lshl_add_u64 v[48:49], s[0:1], 0, v[0:1]
	v_readlane_b32 s0, v249, 6
	v_readlane_b32 s1, v249, 7
	s_mov_b32 s81, 0xfc000
	v_readlane_b32 s41, v250, 9
	v_lshl_add_u64 v[50:51], s[0:1], 0, v[0:1]
	v_readlane_b32 s0, v254, 6
	s_cmp_lg_u32 s32, 0
	s_cselect_b32 s0, 0x600, s0
	v_add_u32_e32 v59, s7, v0
	v_add3_u32 v60, s7, v3, v4
	v_mul_u32_u24_e32 v62, 0x84, v34
	v_or_b32_e32 v63, 8, v34
	v_or_b32_e32 v64, 16, v34
	v_or_b32_e32 v65, 24, v34
	v_mul_u32_u24_e32 v66, 0x84, v2
	v_mov_b32_e32 v35, v1
	s_lshl_b32 s7, s6, 5
	s_lshl_b32 s26, s0, 5
	s_lshl_b32 s27, s6, 1
	s_lshl_b32 s28, s0, 1
	s_mov_b32 s29, s6
	v_readlane_b32 s30, v253, 11
	v_readlane_b32 s31, v253, 12
	v_readlane_b32 s49, v249, 39
	v_readlane_b32 s50, v249, 40
	v_readlane_b32 s51, v249, 41
	v_readlane_b32 s52, v249, 42
	v_readlane_b32 s53, v249, 43
	v_readlane_b32 s82, v250, 6
	v_readlane_b32 s83, v250, 7
	v_readlane_b32 s65, v254, 9
	v_readlane_b32 s66, v254, 10
	v_readlane_b32 s67, v254, 11
	v_readlane_b32 s70, v254, 14
	v_readlane_b32 s71, v254, 15
	v_readlane_b32 s72, v254, 16
	v_readlane_b32 s73, v254, 17
	v_readlane_b32 s74, v254, 18
	v_readlane_b32 s75, v254, 19
	v_readlane_b32 s76, v254, 20
	v_readlane_b32 s77, v254, 21
	v_readlane_b32 s78, v254, 22
	v_readlane_b32 s79, v254, 23
	v_readlane_b32 s1, v254, 7
	s_branch .LBB0_495

.LBB0_494:
	v_readlane_b32 s0, v254, 6
	s_cmp_lg_u32 s32, 0
	s_cselect_b32 s0, 0x600, s0
	s_add_i32 s29, s29, s0
	s_add_i32 s7, s7, s26
	s_add_i32 s27, s27, s28
	s_movk_i32 s0, 0x127f
	s_cmp_lg_u32 s32, 0
	s_cselect_b32 s0, 0x367f, s0
	s_cmp_gt_i32 s29, s0
	v_readlane_b32 s1, v254, 7
	s_cbranch_scc1 .LBB0_605

.LBB0_605:
	v_readlane_b32 s0, v252, 37
	s_waitcnt lgkmcnt(0)
	s_nop 0
	v_add_u32_e32 v2, s0, v58
	s_mov_b32 s0, 0x10000
	v_cmp_gt_i32_e32 vcc, s0, v2
	s_cmp_lg_u32 s32, 0
	s_cselect_b64 vcc, 0, vcc
	s_and_saveexec_b64 s[2:3], vcc
	v_readlane_b32 s20, v254, 24
	v_readlane_b32 s28, v254, 27
	v_readlane_b32 s10, v252, 63
	v_readlane_b32 s40, v254, 38
	v_readlane_b32 s21, v254, 25
	v_readlane_b32 s29, v254, 28
	v_readlane_b32 s11, v253, 0
	s_movk_i32 s26, 0x110
	s_mov_b32 s19, 0x400000
	s_mov_b64 s[82:83], s[4:5]
	v_readlane_b32 s41, v254, 39
	v_readlane_b32 s42, v254, 40
	v_readlane_b32 s43, v254, 41
	v_readlane_b32 s4, v254, 2
	v_readlane_b32 s5, v254, 3
	s_cbranch_execz .LBB0_613
	v_readlane_b32 s0, v252, 38
	s_mov_b64 s[8:9], -1
	s_nop 0
	v_add_u32_e32 v0, s0, v58
	s_mov_b32 s0, 0x10000
	v_max_i32_e32 v3, 0x10000, v0
	v_cmp_gt_i32_e64 s[0:1], s0, v0
	s_nop 1
	v_cndmask_b32_e64 v4, 1, 2, s[0:1]
	v_subb_co_u32_e64 v0, s[0:1], v3, v0, s[0:1]
	v_mul_hi_u32 v3, v0, v217
	v_mul_lo_u32 v5, v3, s4
	v_sub_u32_e32 v0, v0, v5
	v_add_u32_e32 v5, 1, v3
	v_cmp_le_u32_e64 s[0:1], s4, v0
	s_nop 1
	v_cndmask_b32_e64 v3, v3, v5, s[0:1]
	v_subrev_u32_e32 v5, s4, v0
	v_cndmask_b32_e64 v0, v0, v5, s[0:1]
	v_add_u32_e32 v5, 1, v3
	v_cmp_le_u32_e64 s[0:1], s4, v0
	s_nop 1
	v_cndmask_b32_e64 v0, v3, v5, s[0:1]
	v_add_u32_e32 v6, v4, v0
	v_cmp_lt_u32_e64 s[0:1], 1, v6
	v_mov_b32_e32 v4, v2
	s_and_saveexec_b64 s[4:5], s[0:1]
	s_cbranch_execz .LBB0_610
	v_readlane_b32 s0, v252, 32
	v_and_b32_e32 v7, -2, v6
	v_readlane_b32 s1, v252, 33
	v_readlane_b32 s14, v250, 12
	v_add_u32_e32 v0, s0, v2
	v_add_u32_e32 v3, s1, v2
	s_mov_b64 s[8:9], 0
	v_mov_b32_e32 v4, v7
	v_readlane_b32 s7, v253, 49
	v_readlane_b32 s12, v254, 29
	v_readlane_b32 s15, v250, 13

.LBB0_613:
	s_or_b64 exec, exec, s[2:3]
	s_cmp_lg_u32 s32, 0
	s_cbranch_scc1 .LBB0_627
	s_add_i32 s0, s42, 14
	s_cmp_gt_u32 s0, 28
	s_cbranch_scc1 .LBB0_627
	s_and_saveexec_b64 s[2:3], vcc
	v_readlane_b32 s4, v254, 2
	v_readlane_b32 s5, v254, 3
	s_cbranch_execz .LBB0_622
	v_readlane_b32 s0, v252, 38
	s_nop 1
	v_add_u32_e32 v0, s0, v58
	s_mov_b32 s0, 0x10000
	v_max_i32_e32 v3, 0x10000, v0
	v_cmp_gt_i32_e32 vcc, s0, v0
	s_mov_b64 s[0:1], -1
	s_nop 0
	v_cndmask_b32_e64 v4, 1, 2, vcc
	v_subb_co_u32_e32 v0, vcc, v3, v0, vcc
	v_mul_hi_u32 v3, v0, v217
	v_mul_lo_u32 v5, v3, s4
	v_sub_u32_e32 v0, v0, v5
	v_add_u32_e32 v5, 1, v3
	v_cmp_le_u32_e32 vcc, s4, v0
	s_nop 1
	v_cndmask_b32_e32 v3, v3, v5, vcc
	v_subrev_u32_e32 v5, s4, v0
	v_cndmask_b32_e32 v0, v0, v5, vcc
	v_add_u32_e32 v5, 1, v3
	v_cmp_le_u32_e32 vcc, s4, v0
	s_nop 1
	v_cndmask_b32_e32 v0, v3, v5, vcc
	v_add_u32_e32 v4, v4, v0
	v_cmp_lt_u32_e32 vcc, 1, v4
	s_and_saveexec_b64 s[4:5], vcc
	s_cbranch_execz .LBB0_619
	v_readlane_b32 s0, v252, 32
	v_and_b32_e32 v5, -2, v4
	v_readlane_b32 s1, v252, 33
	v_add_u32_e32 v0, s0, v2
	s_mov_b64 s[8:9], 0
	v_add_u32_e32 v3, s1, v2
	v_mov_b32_e32 v6, v5
	v_readlane_b32 s7, v253, 49
	v_readlane_b32 s12, v254, 29
